# tail-fill conversion throttled: only 4 of the 8 waves of each idle workgroup convert (lower HBM queueing for the GEMM tail round)
# baseline (speedup 1.0000x reference)
.LBB0_302:
	s_cmpk_lg_i32 s33, 0x100
	s_cbranch_scc1 .Lmy_skip_p2
	s_cmp_lt_u32 s76, 108
	s_cbranch_scc1 .Lmy_skip_p2
	s_waitcnt vmcnt(0) lgkmcnt(0)
	s_barrier
	s_cmp_ge_u32 s25, 4
	s_cbranch_scc1 .Lmy_skip_p2
	v_writelane_b32 v255, s0, 0
	v_writelane_b32 v255, s1, 1
	v_writelane_b32 v255, s2, 2
	v_writelane_b32 v255, s3, 3
	v_writelane_b32 v255, s4, 4
	v_writelane_b32 v255, s5, 5
	v_writelane_b32 v255, s6, 6
	v_writelane_b32 v255, s7, 7
	v_writelane_b32 v255, s8, 8
	v_writelane_b32 v255, s9, 9
	v_writelane_b32 v255, s10, 10
	v_writelane_b32 v255, s11, 11
	v_writelane_b32 v255, s12, 12
	v_writelane_b32 v255, s13, 13
	v_writelane_b32 v255, s14, 14
	v_writelane_b32 v255, s15, 15
	v_writelane_b32 v255, s16, 16
	v_writelane_b32 v255, s17, 17
	v_writelane_b32 v255, s18, 18
	v_writelane_b32 v255, s19, 19
	v_writelane_b32 v255, s20, 20
	v_writelane_b32 v255, s21, 21
	v_writelane_b32 v255, s22, 22
	v_writelane_b32 v255, s23, 23
	v_writelane_b32 v255, s26, 24
	v_writelane_b32 v255, s27, 25
	v_writelane_b32 v255, s34, 26
	v_writelane_b32 v255, s35, 27
	v_writelane_b32 v255, s36, 28
	v_writelane_b32 v255, s37, 29
	v_writelane_b32 v255, s38, 30
	v_writelane_b32 v255, s39, 31
	v_writelane_b32 v255, s40, 32
	v_writelane_b32 v255, s41, 33
	v_writelane_b32 v255, s42, 34
	v_writelane_b32 v255, s43, 35
	v_writelane_b32 v255, s44, 36
	v_writelane_b32 v255, s45, 37
	v_writelane_b32 v255, s46, 38
	v_writelane_b32 v255, s47, 39
	v_writelane_b32 v255, s48, 40
	v_writelane_b32 v255, s49, 41
	v_writelane_b32 v255, s50, 42
	v_writelane_b32 v255, s51, 43
	v_writelane_b32 v255, s52, 44
	v_writelane_b32 v255, s53, 45
	v_writelane_b32 v255, s54, 46
	v_writelane_b32 v255, s55, 47
	v_writelane_b32 v255, s56, 48
	v_writelane_b32 v255, s57, 49
	v_writelane_b32 v255, s58, 50
	v_writelane_b32 v255, s59, 51
	v_writelane_b32 v255, s60, 52
	v_writelane_b32 v255, s61, 53
	v_writelane_b32 v255, s62, 54
	v_writelane_b32 v255, s63, 55
	v_writelane_b32 v255, s64, 56
	v_writelane_b32 v255, s65, 57
	v_writelane_b32 v255, s66, 58
	v_writelane_b32 v255, s67, 59
	v_writelane_b32 v255, s68, 60
	v_writelane_b32 v255, s69, 61
	v_writelane_b32 v255, s70, 62
	v_writelane_b32 v255, s71, 63
	v_writelane_b32 v254, s76, 0
	v_writelane_b32 v254, s77, 1
	v_writelane_b32 v254, s80, 2
	v_writelane_b32 v254, s81, 3
	v_writelane_b32 v254, s82, 4
	v_writelane_b32 v254, s83, 5
	v_writelane_b32 v254, s84, 6
	v_writelane_b32 v254, s85, 7
	v_writelane_b32 v254, s86, 8
	v_writelane_b32 v254, s87, 9
	v_writelane_b32 v254, s88, 10
	v_writelane_b32 v254, s89, 11
	v_writelane_b32 v254, s90, 12
	v_writelane_b32 v254, s91, 13
	v_writelane_b32 v254, s92, 14
	v_writelane_b32 v254, s93, 15
	v_writelane_b32 v254, s94, 16
	v_writelane_b32 v254, s95, 17
	v_writelane_b32 v254, s96, 18
	v_writelane_b32 v254, s97, 19
	s_sub_i32 s98, s76, 108
	s_lshl_b32 s98, s98, 2
	s_add_i32 s98, s98, s25
	s_add_i32 s98, s98, 0x6180
	s_movk_i32 s99, 0x250
	s_mov_b32 s100, 0x8c80
	s_mov_b32 s101, 1
	s_add_u32 s0, s78, 0xfffffef0
	s_addc_u32 s1, s79, -1
	s_load_dwordx8 s[36:43], s[0:1], 0x40
	s_waitcnt lgkmcnt(0)
	s_branch .Lmy_cvt_entry

.LBB0_716:
	s_waitcnt vmcnt(0)
	s_barrier
	s_cmpk_lg_i32 s33, 0x100
	s_cbranch_scc1 .Lmy_skip_p5
	s_cmp_lt_u32 s76, 164
	s_cbranch_scc1 .Lmy_skip_p5
	s_waitcnt vmcnt(0) lgkmcnt(0)
	s_barrier
	s_cmp_ge_u32 s25, 4
	s_cbranch_scc1 .Lmy_skip_p5
	v_writelane_b32 v255, s0, 0
	v_writelane_b32 v255, s1, 1
	v_writelane_b32 v255, s2, 2
	v_writelane_b32 v255, s3, 3
	v_writelane_b32 v255, s4, 4
	v_writelane_b32 v255, s5, 5
	v_writelane_b32 v255, s6, 6
	v_writelane_b32 v255, s7, 7
	v_writelane_b32 v255, s8, 8
	v_writelane_b32 v255, s9, 9
	v_writelane_b32 v255, s10, 10
	v_writelane_b32 v255, s11, 11
	v_writelane_b32 v255, s12, 12
	v_writelane_b32 v255, s13, 13
	v_writelane_b32 v255, s14, 14
	v_writelane_b32 v255, s15, 15
	v_writelane_b32 v255, s16, 16
	v_writelane_b32 v255, s17, 17
	v_writelane_b32 v255, s18, 18
	v_writelane_b32 v255, s19, 19
	v_writelane_b32 v255, s20, 20
	v_writelane_b32 v255, s21, 21
	v_writelane_b32 v255, s22, 22
	v_writelane_b32 v255, s23, 23
	v_writelane_b32 v255, s26, 24
	v_writelane_b32 v255, s27, 25
	v_writelane_b32 v255, s34, 26
	v_writelane_b32 v255, s35, 27
	v_writelane_b32 v255, s36, 28
	v_writelane_b32 v255, s37, 29
	v_writelane_b32 v255, s38, 30
	v_writelane_b32 v255, s39, 31
	v_writelane_b32 v255, s40, 32
	v_writelane_b32 v255, s41, 33
	v_writelane_b32 v255, s42, 34
	v_writelane_b32 v255, s43, 35
	v_writelane_b32 v255, s44, 36
	v_writelane_b32 v255, s45, 37
	v_writelane_b32 v255, s46, 38
	v_writelane_b32 v255, s47, 39
	v_writelane_b32 v255, s48, 40
	v_writelane_b32 v255, s49, 41
	v_writelane_b32 v255, s50, 42
	v_writelane_b32 v255, s51, 43
	v_writelane_b32 v255, s52, 44
	v_writelane_b32 v255, s53, 45
	v_writelane_b32 v255, s54, 46
	v_writelane_b32 v255, s55, 47
	v_writelane_b32 v255, s56, 48
	v_writelane_b32 v255, s57, 49
	v_writelane_b32 v255, s58, 50
	v_writelane_b32 v255, s59, 51
	v_writelane_b32 v255, s60, 52
	v_writelane_b32 v255, s61, 53
	v_writelane_b32 v255, s62, 54
	v_writelane_b32 v255, s63, 55
	v_writelane_b32 v255, s64, 56
	v_writelane_b32 v255, s65, 57
	v_writelane_b32 v255, s66, 58
	v_writelane_b32 v255, s67, 59
	v_writelane_b32 v255, s68, 60
	v_writelane_b32 v255, s69, 61
	v_writelane_b32 v255, s70, 62
	v_writelane_b32 v255, s71, 63
	v_writelane_b32 v254, s76, 0
	v_writelane_b32 v254, s77, 1
	v_writelane_b32 v254, s80, 2
	v_writelane_b32 v254, s81, 3
	v_writelane_b32 v254, s82, 4
	v_writelane_b32 v254, s83, 5
	v_writelane_b32 v254, s84, 6
	v_writelane_b32 v254, s85, 7
	v_writelane_b32 v254, s86, 8
	v_writelane_b32 v254, s87, 9
	v_writelane_b32 v254, s88, 10
	v_writelane_b32 v254, s89, 11
	v_writelane_b32 v254, s90, 12
	v_writelane_b32 v254, s91, 13
	v_writelane_b32 v254, s92, 14
	v_writelane_b32 v254, s93, 15
	v_writelane_b32 v254, s94, 16
	v_writelane_b32 v254, s95, 17
	v_writelane_b32 v254, s96, 18
	v_writelane_b32 v254, s97, 19
	s_sub_i32 s98, s76, 164
	s_lshl_b32 s98, s98, 2
	s_add_i32 s98, s98, s25
	s_add_i32 s98, s98, 0x8c80
	s_movk_i32 s99, 0x170
	s_mov_b32 s100, 0xa200
	s_mov_b32 s101, 2
	s_add_u32 s0, s78, 0xfffffef0
	s_addc_u32 s1, s79, -1
	s_load_dwordx8 s[36:43], s[0:1], 0x40
	s_waitcnt lgkmcnt(0)
	s_branch .Lmy_cvt_entry

.LBB0_1571:
	s_cmpk_lg_i32 s33, 0x100
	s_cbranch_scc1 .Lmy_skip_p11
	s_cmp_lt_u32 s76, 108
	s_cbranch_scc1 .Lmy_skip_p11
	s_waitcnt vmcnt(0) lgkmcnt(0)
	s_barrier
	s_cmp_ge_u32 s25, 4
	s_cbranch_scc1 .Lmy_skip_p11
	v_writelane_b32 v255, s0, 0
	v_writelane_b32 v255, s1, 1
	v_writelane_b32 v255, s2, 2
	v_writelane_b32 v255, s3, 3
	v_writelane_b32 v255, s4, 4
	v_writelane_b32 v255, s5, 5
	v_writelane_b32 v255, s6, 6
	v_writelane_b32 v255, s7, 7
	v_writelane_b32 v255, s8, 8
	v_writelane_b32 v255, s9, 9
	v_writelane_b32 v255, s10, 10
	v_writelane_b32 v255, s11, 11
	v_writelane_b32 v255, s12, 12
	v_writelane_b32 v255, s13, 13
	v_writelane_b32 v255, s14, 14
	v_writelane_b32 v255, s15, 15
	v_writelane_b32 v255, s16, 16
	v_writelane_b32 v255, s17, 17
	v_writelane_b32 v255, s18, 18
	v_writelane_b32 v255, s19, 19
	v_writelane_b32 v255, s20, 20
	v_writelane_b32 v255, s21, 21
	v_writelane_b32 v255, s22, 22
	v_writelane_b32 v255, s23, 23
	v_writelane_b32 v255, s26, 24
	v_writelane_b32 v255, s27, 25
	v_writelane_b32 v255, s34, 26
	v_writelane_b32 v255, s35, 27
	v_writelane_b32 v255, s36, 28
	v_writelane_b32 v255, s37, 29
	v_writelane_b32 v255, s38, 30
	v_writelane_b32 v255, s39, 31
	v_writelane_b32 v255, s40, 32
	v_writelane_b32 v255, s41, 33
	v_writelane_b32 v255, s42, 34
	v_writelane_b32 v255, s43, 35
	v_writelane_b32 v255, s44, 36
	v_writelane_b32 v255, s45, 37
	v_writelane_b32 v255, s46, 38
	v_writelane_b32 v255, s47, 39
	v_writelane_b32 v255, s48, 40
	v_writelane_b32 v255, s49, 41
	v_writelane_b32 v255, s50, 42
	v_writelane_b32 v255, s51, 43
	v_writelane_b32 v255, s52, 44
	v_writelane_b32 v255, s53, 45
	v_writelane_b32 v255, s54, 46
	v_writelane_b32 v255, s55, 47
	v_writelane_b32 v255, s56, 48
	v_writelane_b32 v255, s57, 49
	v_writelane_b32 v255, s58, 50
	v_writelane_b32 v255, s59, 51
	v_writelane_b32 v255, s60, 52
	v_writelane_b32 v255, s61, 53
	v_writelane_b32 v255, s62, 54
	v_writelane_b32 v255, s63, 55
	v_writelane_b32 v255, s64, 56
	v_writelane_b32 v255, s65, 57
	v_writelane_b32 v255, s66, 58
	v_writelane_b32 v255, s67, 59
	v_writelane_b32 v255, s68, 60
	v_writelane_b32 v255, s69, 61
	v_writelane_b32 v255, s70, 62
	v_writelane_b32 v255, s71, 63
	v_writelane_b32 v254, s76, 0
	v_writelane_b32 v254, s77, 1
	v_writelane_b32 v254, s80, 2
	v_writelane_b32 v254, s81, 3
	v_writelane_b32 v254, s82, 4
	v_writelane_b32 v254, s83, 5
	v_writelane_b32 v254, s84, 6
	v_writelane_b32 v254, s85, 7
	v_writelane_b32 v254, s86, 8
	v_writelane_b32 v254, s87, 9
	v_writelane_b32 v254, s88, 10
	v_writelane_b32 v254, s89, 11
	v_writelane_b32 v254, s90, 12
	v_writelane_b32 v254, s91, 13
	v_writelane_b32 v254, s92, 14
	v_writelane_b32 v254, s93, 15
	v_writelane_b32 v254, s94, 16
	v_writelane_b32 v254, s95, 17
	v_writelane_b32 v254, s96, 18
	v_writelane_b32 v254, s97, 19
	s_sub_i32 s98, s76, 108
	s_lshl_b32 s98, s98, 2
	s_add_i32 s98, s98, s25
	s_add_i32 s98, s98, 0xa200
	s_movk_i32 s99, 0x250
	s_mov_b32 s100, 0xcd00
	s_mov_b32 s101, 3
	s_add_u32 s0, s78, 0xfffffef0
	s_addc_u32 s1, s79, -1
	s_load_dwordx8 s[36:43], s[0:1], 0x40
	s_waitcnt lgkmcnt(0)
	s_branch .Lmy_h1_fwd

.LBB0_1891:
	s_cmpk_lg_i32 s33, 0x100
	s_cbranch_scc1 .Lmy_skip_p14
	s_cmp_lt_u32 s76, 108
	s_cbranch_scc1 .Lmy_skip_p14
	s_waitcnt vmcnt(0) lgkmcnt(0)
	s_barrier
	s_cmp_ge_u32 s25, 4
	s_cbranch_scc1 .Lmy_skip_p14
	v_writelane_b32 v255, s0, 0
	v_writelane_b32 v255, s1, 1
	v_writelane_b32 v255, s2, 2
	v_writelane_b32 v255, s3, 3
	v_writelane_b32 v255, s4, 4
	v_writelane_b32 v255, s5, 5
	v_writelane_b32 v255, s6, 6
	v_writelane_b32 v255, s7, 7
	v_writelane_b32 v255, s8, 8
	v_writelane_b32 v255, s9, 9
	v_writelane_b32 v255, s10, 10
	v_writelane_b32 v255, s11, 11
	v_writelane_b32 v255, s12, 12
	v_writelane_b32 v255, s13, 13
	v_writelane_b32 v255, s14, 14
	v_writelane_b32 v255, s15, 15
	v_writelane_b32 v255, s16, 16
	v_writelane_b32 v255, s17, 17
	v_writelane_b32 v255, s18, 18
	v_writelane_b32 v255, s19, 19
	v_writelane_b32 v255, s20, 20
	v_writelane_b32 v255, s21, 21
	v_writelane_b32 v255, s22, 22
	v_writelane_b32 v255, s23, 23
	v_writelane_b32 v255, s26, 24
	v_writelane_b32 v255, s27, 25
	v_writelane_b32 v255, s34, 26
	v_writelane_b32 v255, s35, 27
	v_writelane_b32 v255, s36, 28
	v_writelane_b32 v255, s37, 29
	v_writelane_b32 v255, s38, 30
	v_writelane_b32 v255, s39, 31
	v_writelane_b32 v255, s40, 32
	v_writelane_b32 v255, s41, 33
	v_writelane_b32 v255, s42, 34
	v_writelane_b32 v255, s43, 35
	v_writelane_b32 v255, s44, 36
	v_writelane_b32 v255, s45, 37
	v_writelane_b32 v255, s46, 38
	v_writelane_b32 v255, s47, 39
	v_writelane_b32 v255, s48, 40
	v_writelane_b32 v255, s49, 41
	v_writelane_b32 v255, s50, 42
	v_writelane_b32 v255, s51, 43
	v_writelane_b32 v255, s52, 44
	v_writelane_b32 v255, s53, 45
	v_writelane_b32 v255, s54, 46
	v_writelane_b32 v255, s55, 47
	v_writelane_b32 v255, s56, 48
	v_writelane_b32 v255, s57, 49
	v_writelane_b32 v255, s58, 50
	v_writelane_b32 v255, s59, 51
	v_writelane_b32 v255, s60, 52
	v_writelane_b32 v255, s61, 53
	v_writelane_b32 v255, s62, 54
	v_writelane_b32 v255, s63, 55
	v_writelane_b32 v255, s64, 56
	v_writelane_b32 v255, s65, 57
	v_writelane_b32 v255, s66, 58
	v_writelane_b32 v255, s67, 59
	v_writelane_b32 v255, s68, 60
	v_writelane_b32 v255, s69, 61
	v_writelane_b32 v255, s70, 62
	v_writelane_b32 v255, s71, 63
	v_writelane_b32 v254, s76, 0
	v_writelane_b32 v254, s77, 1
	v_writelane_b32 v254, s80, 2
	v_writelane_b32 v254, s81, 3
	v_writelane_b32 v254, s82, 4
	v_writelane_b32 v254, s83, 5
	v_writelane_b32 v254, s84, 6
	v_writelane_b32 v254, s85, 7
	v_writelane_b32 v254, s86, 8
	v_writelane_b32 v254, s87, 9
	v_writelane_b32 v254, s88, 10
	v_writelane_b32 v254, s89, 11
	v_writelane_b32 v254, s90, 12
	v_writelane_b32 v254, s91, 13
	v_writelane_b32 v254, s92, 14
	v_writelane_b32 v254, s93, 15
	v_writelane_b32 v254, s94, 16
	v_writelane_b32 v254, s95, 17
	v_writelane_b32 v254, s96, 18
	v_writelane_b32 v254, s97, 19
	s_sub_i32 s98, s76, 108
	s_lshl_b32 s98, s98, 2
	s_add_i32 s98, s98, s25
	s_add_i32 s98, s98, 0xcd00
	s_movk_i32 s99, 0x250
	s_mov_b32 s100, 0xfa00
	s_mov_b32 s101, 4
	s_add_u32 s0, s78, 0xfffffef0
	s_addc_u32 s1, s79, -1
	s_load_dwordx8 s[36:43], s[0:1], 0x40
	s_waitcnt lgkmcnt(0)
	s_branch .Lmy_h2_fwd

.LBB0_2241:
	s_waitcnt vmcnt(0)
	s_barrier
	s_cmpk_lg_i32 s33, 0x100
	s_cbranch_scc1 .Lmy_skip_p17
	s_cmp_lt_u32 s76, 48
	s_cbranch_scc1 .Lmy_skip_p17
	s_waitcnt vmcnt(0) lgkmcnt(0)
	s_barrier
	s_cmp_ge_u32 s25, 4
	s_cbranch_scc1 .Lmy_skip_p17
	v_writelane_b32 v255, s0, 0
	v_writelane_b32 v255, s1, 1
	v_writelane_b32 v255, s2, 2
	v_writelane_b32 v255, s3, 3
	v_writelane_b32 v255, s4, 4
	v_writelane_b32 v255, s5, 5
	v_writelane_b32 v255, s6, 6
	v_writelane_b32 v255, s7, 7
	v_writelane_b32 v255, s8, 8
	v_writelane_b32 v255, s9, 9
	v_writelane_b32 v255, s10, 10
	v_writelane_b32 v255, s11, 11
	v_writelane_b32 v255, s12, 12
	v_writelane_b32 v255, s13, 13
	v_writelane_b32 v255, s14, 14
	v_writelane_b32 v255, s15, 15
	v_writelane_b32 v255, s16, 16
	v_writelane_b32 v255, s17, 17
	v_writelane_b32 v255, s18, 18
	v_writelane_b32 v255, s19, 19
	v_writelane_b32 v255, s20, 20
	v_writelane_b32 v255, s21, 21
	v_writelane_b32 v255, s22, 22
	v_writelane_b32 v255, s23, 23
	v_writelane_b32 v255, s26, 24
	v_writelane_b32 v255, s27, 25
	v_writelane_b32 v255, s34, 26
	v_writelane_b32 v255, s35, 27
	v_writelane_b32 v255, s36, 28
	v_writelane_b32 v255, s37, 29
	v_writelane_b32 v255, s38, 30
	v_writelane_b32 v255, s39, 31
	v_writelane_b32 v255, s40, 32
	v_writelane_b32 v255, s41, 33
	v_writelane_b32 v255, s42, 34
	v_writelane_b32 v255, s43, 35
	v_writelane_b32 v255, s44, 36
	v_writelane_b32 v255, s45, 37
	v_writelane_b32 v255, s46, 38
	v_writelane_b32 v255, s47, 39
	v_writelane_b32 v255, s48, 40
	v_writelane_b32 v255, s49, 41
	v_writelane_b32 v255, s50, 42
	v_writelane_b32 v255, s51, 43
	v_writelane_b32 v255, s52, 44
	v_writelane_b32 v255, s53, 45
	v_writelane_b32 v255, s54, 46
	v_writelane_b32 v255, s55, 47
	v_writelane_b32 v255, s56, 48
	v_writelane_b32 v255, s57, 49
	v_writelane_b32 v255, s58, 50
	v_writelane_b32 v255, s59, 51
	v_writelane_b32 v255, s60, 52
	v_writelane_b32 v255, s61, 53
	v_writelane_b32 v255, s62, 54
	v_writelane_b32 v255, s63, 55
	v_writelane_b32 v255, s64, 56
	v_writelane_b32 v255, s65, 57
	v_writelane_b32 v255, s66, 58
	v_writelane_b32 v255, s67, 59
	v_writelane_b32 v255, s68, 60
	v_writelane_b32 v255, s69, 61
	v_writelane_b32 v255, s70, 62
	v_writelane_b32 v255, s71, 63
	v_writelane_b32 v254, s76, 0
	v_writelane_b32 v254, s77, 1
	v_writelane_b32 v254, s80, 2
	v_writelane_b32 v254, s81, 3
	v_writelane_b32 v254, s82, 4
	v_writelane_b32 v254, s83, 5
	v_writelane_b32 v254, s84, 6
	v_writelane_b32 v254, s85, 7
	v_writelane_b32 v254, s86, 8
	v_writelane_b32 v254, s87, 9
	v_writelane_b32 v254, s88, 10
	v_writelane_b32 v254, s89, 11
	v_writelane_b32 v254, s90, 12
	v_writelane_b32 v254, s91, 13
	v_writelane_b32 v254, s92, 14
	v_writelane_b32 v254, s93, 15
	v_writelane_b32 v254, s94, 16
	v_writelane_b32 v254, s95, 17
	v_writelane_b32 v254, s96, 18
	v_writelane_b32 v254, s97, 19
	s_sub_i32 s98, s76, 48
	s_lshl_b32 s98, s98, 2
	s_add_i32 s98, s98, s25
	s_add_i32 s98, s98, 0xfa00
	s_movk_i32 s99, 0x340
	s_mov_b32 s100, 0x13a80
	s_mov_b32 s101, 5
	s_add_u32 s0, s78, 0xfffffef0
	s_addc_u32 s1, s79, -1
	s_load_dwordx8 s[36:43], s[0:1], 0x40
	s_waitcnt lgkmcnt(0)
	s_branch .Lmy_h2_fwd
